# v51 + counted waits at the mLSTM / RG-LRU chunk boundaries (result stores and head-norm atomic no longer drained for chunks >= 1)
# speedup vs baseline: 1.0223x; 1.0190x over previous
; DI void lru_unit(const Params& p, unsigned char* smem, int unit) {
;     ...
;     float br[4], bi[4], sp[4];
; #pragma unroll
;     for (int j = 0; j < 4; ++j) {
;         const int ch = n * 128 + half * 64 + et * 16 + fq * 4 + j;
;         br[j] = p.b_r[ch]; bi[j] = p.b_i[ch];
;         const float l = p.lam[ch];
;         sp[j] = fmaxf(-l, 0.f) + log1pf(__expf(-fabsf(l)));
;     }
.LBB0_336:
	s_or_b64 exec, exec, s[0:1]
	s_mov_b32 s9, 0xbfb8aa3b
	s_waitcnt vmcnt(1)
	v_mul_f32_e64 v72, |v64|, s9
	v_exp_f32_e32 v81, v72
	v_max_f32_e64 v64, -v64, -v64
	v_max_f32_e32 v73, 0, v64
	s_mov_b32 s10, 0x3f2aaaab
	v_add_f32_e32 v110, 1.0, v81
	v_add_f32_e32 v64, -1.0, v110
	v_sub_f32_e32 v72, v64, v110
	v_add_f32_e32 v72, 1.0, v72
	v_sub_f32_e32 v64, v81, v64
	v_add_f32_e32 v111, v64, v72
	v_mul_f32_e64 v64, |v65|, s9
	v_exp_f32_e32 v72, v64
	v_cvt_f64_f32_e32 v[82:83], v110
	v_max_f32_e64 v64, -v65, -v65
	v_frexp_exp_i32_f64_e32 v113, v[82:83]
	v_add_f32_e32 v84, 1.0, v72
	v_add_f32_e32 v65, -1.0, v84
	v_sub_f32_e32 v82, v65, v84
	v_add_f32_e32 v82, 1.0, v82
	v_sub_f32_e32 v65, v72, v65
	v_add_f32_e32 v85, v65, v82
	v_mul_f32_e64 v65, |v66|, s9
	v_exp_f32_e32 v114, v65
	v_cvt_f64_f32_e32 v[82:83], v84
	v_max_f32_e64 v65, -v66, -v66
	v_frexp_exp_i32_f64_e32 v87, v[82:83]
	v_add_f32_e32 v66, 1.0, v114
	v_add_f32_e32 v82, -1.0, v66
	v_sub_f32_e32 v83, v82, v66
	v_add_f32_e32 v83, 1.0, v83
	v_sub_f32_e32 v82, v114, v82
	v_add_f32_e32 v88, v82, v83
	v_frexp_mant_f32_e32 v89, v66
	v_cvt_f64_f32_e32 v[82:83], v66
	v_frexp_exp_i32_f64_e32 v82, v[82:83]
	v_cmp_gt_f32_e32 vcc, s10, v89
	v_frexp_mant_f32_e32 v86, v84
	s_movk_i32 s7, 0x43
	v_subbrev_co_u32_e32 v115, vcc, 0, v82, vcc
	v_cmp_gt_f32_e32 vcc, s10, v86
	s_mov_b32 s6, 0x3ecc95a3
	s_mov_b32 s16, 0x3f2aaada
	v_subbrev_co_u32_e32 v122, vcc, 0, v87, vcc
	v_sub_u32_e32 v83, 0, v122
	v_ldexp_f32 v82, v84, v83
	v_ldexp_f32 v84, v85, v83
	v_sub_u32_e32 v85, 0, v115
	v_ldexp_f32 v83, v66, v85
	v_pk_add_f32 v[86:87], v[82:83], 1.0 op_sel_hi:[1,0]
	v_ldexp_f32 v85, v88, v85
	v_pk_add_f32 v[88:89], v[86:87], -1.0 op_sel_hi:[1,0]
	v_pk_add_f32 v[94:95], v[82:83], -1.0 op_sel_hi:[1,0]
	v_pk_add_f32 v[88:89], v[82:83], v[88:89] neg_lo:[0,1] neg_hi:[0,1]
	v_pk_add_f32 v[96:97], v[94:95], 1.0 op_sel_hi:[1,0]
	v_pk_add_f32 v[88:89], v[84:85], v[88:89]
	v_pk_add_f32 v[82:83], v[82:83], v[96:97] neg_lo:[0,1] neg_hi:[0,1]
	v_pk_add_f32 v[90:91], v[86:87], v[88:89]
	v_pk_add_f32 v[82:83], v[84:85], v[82:83]
	v_rcp_f32_e32 v92, v90
	v_rcp_f32_e32 v93, v91
	v_pk_add_f32 v[84:85], v[94:95], v[82:83]
	v_pk_add_f32 v[86:87], v[90:91], v[86:87] neg_lo:[0,1] neg_hi:[0,1]
	v_pk_add_f32 v[94:95], v[84:85], v[94:95] neg_lo:[0,1] neg_hi:[0,1]
	v_pk_mul_f32 v[96:97], v[84:85], v[92:93]
	v_pk_add_f32 v[86:87], v[88:89], v[86:87] neg_lo:[0,1] neg_hi:[0,1]
	v_pk_mul_f32 v[88:89], v[90:91], v[96:97]
	v_pk_add_f32 v[82:83], v[82:83], v[94:95] neg_lo:[0,1] neg_hi:[0,1]
	v_pk_fma_f32 v[94:95], v[96:97], v[90:91], v[88:89] neg_lo:[0,0,1] neg_hi:[0,0,1]
	s_mov_b32 s20, 0x3f317218
	v_pk_fma_f32 v[94:95], v[96:97], v[86:87], v[94:95]
	s_mov_b32 s22, 0xb102e308
	v_pk_add_f32 v[98:99], v[88:89], v[94:95]
	s_mov_b32 s11, 0x7f800000
	v_pk_add_f32 v[100:101], v[84:85], v[98:99] neg_lo:[0,1] neg_hi:[0,1]
	v_pk_add_f32 v[88:89], v[98:99], v[88:89] neg_lo:[0,1] neg_hi:[0,1]
	v_pk_add_f32 v[84:85], v[84:85], v[100:101] neg_lo:[0,1] neg_hi:[0,1]
	v_cmp_neq_f32_e32 vcc, s11, v72
	v_pk_add_f32 v[84:85], v[84:85], v[98:99] neg_lo:[0,1] neg_hi:[0,1]
	s_mov_b32 s15, 0x33800000
	v_pk_add_f32 v[82:83], v[82:83], v[84:85]
	v_pk_add_f32 v[84:85], v[88:89], v[94:95] neg_lo:[0,1] neg_hi:[0,1]
	v_max_f32_e32 v64, 0, v64
	v_pk_add_f32 v[82:83], v[84:85], v[82:83]
	v_max_f32_e32 v65, 0, v65
	v_pk_add_f32 v[84:85], v[100:101], v[82:83]
	v_frexp_mant_f32_e32 v112, v110
	v_pk_mul_f32 v[88:89], v[92:93], v[84:85]
	v_pk_add_f32 v[100:101], v[100:101], v[84:85] neg_lo:[0,1] neg_hi:[0,1]
	v_pk_mul_f32 v[94:95], v[90:91], v[88:89]
	v_pk_add_f32 v[82:83], v[82:83], v[100:101]
	v_pk_fma_f32 v[90:91], v[88:89], v[90:91], v[94:95] neg_lo:[0,0,1] neg_hi:[0,0,1]
	v_pk_add_f32 v[108:109], v[96:97], v[88:89]
	v_pk_fma_f32 v[86:87], v[88:89], v[86:87], v[90:91]
	v_and_b32_e32 v80, 63, v69
	v_pk_add_f32 v[90:91], v[94:95], v[86:87]
	s_cmp_lt_u32 s13, 16
	v_pk_add_f32 v[102:103], v[84:85], v[90:91] neg_lo:[0,1] neg_hi:[0,1]
	v_pk_add_f32 v[98:99], v[90:91], v[94:95] neg_lo:[0,1] neg_hi:[0,1]
	v_pk_add_f32 v[106:107], v[84:85], v[102:103] neg_lo:[0,1] neg_hi:[0,1]
	v_mov_b32_e32 v84, v91
	v_mov_b32_e32 v94, v95
	v_mov_b32_e32 v95, v103
	v_pk_add_f32 v[106:107], v[106:107], v[90:91] neg_lo:[0,1] neg_hi:[0,1]
	v_pk_add_f32 v[84:85], v[84:85], v[94:95] neg_lo:[0,1] neg_hi:[0,1]
	v_mov_b32_e32 v90, v87
	v_pk_add_f32 v[84:85], v[84:85], v[90:91] neg_lo:[0,1] neg_hi:[0,1]
	v_pk_add_f32 v[98:99], v[98:99], v[86:87] neg_lo:[0,1] neg_hi:[0,1]
	v_mov_b32_e32 v107, v85
	v_pk_add_f32 v[82:83], v[82:83], v[106:107]
	v_mov_b32_e32 v99, v84
	v_pk_add_f32 v[82:83], v[98:99], v[82:83]
	v_pk_add_f32 v[84:85], v[108:109], v[96:97] neg_lo:[0,1] neg_hi:[0,1]
	v_pk_add_f32 v[82:83], v[102:103], v[82:83]
	v_pk_add_f32 v[84:85], v[88:89], v[84:85] neg_lo:[0,1] neg_hi:[0,1]
	v_pk_mul_f32 v[82:83], v[92:93], v[82:83]
	v_mov_b64_e32 v[92:93], s[6:7]
	v_pk_add_f32 v[82:83], v[84:85], v[82:83]
	s_mov_b32 s6, 0x3e9b6dac
	v_pk_add_f32 v[84:85], v[108:109], v[82:83]
	v_cvt_f32_i32_e32 v91, v115
	v_pk_mul_f32 v[88:89], v[84:85], v[84:85]
	v_pk_add_f32 v[86:87], v[84:85], v[108:109] neg_lo:[0,1] neg_hi:[0,1]
	v_pk_fma_f32 v[94:95], v[88:89], s[6:7], v[92:93] op_sel_hi:[1,0,0]
	v_pk_add_f32 v[82:83], v[82:83], v[86:87] neg_lo:[0,1] neg_hi:[0,1]
	v_ldexp_f32 v86, v84, 1
	v_cvt_f32_i32_e32 v90, v122
	v_pk_fma_f32 v[94:95], v[88:89], v[94:95], s[16:17] op_sel_hi:[1,1,0]
	v_ldexp_f32 v87, v85, 1
	v_pk_mul_f32 v[84:85], v[84:85], v[88:89]
	v_ldexp_f32 v82, v82, 1
	v_pk_mul_f32 v[84:85], v[84:85], v[94:95]
	v_pk_mul_f32 v[96:97], v[90:91], s[20:21] op_sel_hi:[1,0]
	v_pk_add_f32 v[88:89], v[86:87], v[84:85]
; DI void lru_unit(const Params& p, unsigned char* smem, int unit) {
;     ...
;     float br[4], bi[4], sp[4];
; #pragma unroll
;     for (int j = 0; j < 4; ++j) {
;         const int ch = n * 128 + half * 64 + et * 16 + fq * 4 + j;
;         br[j] = p.b_r[ch]; bi[j] = p.b_i[ch];
;         const float l = p.lam[ch];
;         sp[j] = fmaxf(-l, 0.f) + log1pf(__expf(-fabsf(l)));
;     }
	v_ldexp_f32 v83, v83, 1
	v_pk_add_f32 v[86:87], v[88:89], v[86:87] neg_lo:[0,1] neg_hi:[0,1]
	v_pk_fma_f32 v[98:99], v[90:91], s[20:21], v[96:97] op_sel_hi:[1,0,1] neg_lo:[0,0,1] neg_hi:[0,0,1]
	v_pk_add_f32 v[84:85], v[84:85], v[86:87] neg_lo:[0,1] neg_hi:[0,1]
	v_pk_fma_f32 v[90:91], v[90:91], s[22:23], v[98:99] op_sel_hi:[1,0,1]
	v_pk_add_f32 v[82:83], v[82:83], v[84:85]
	v_pk_add_f32 v[98:99], v[96:97], v[90:91]
	v_pk_add_f32 v[84:85], v[88:89], v[82:83]
	v_pk_add_f32 v[96:97], v[98:99], v[96:97] neg_lo:[0,1] neg_hi:[0,1]
	v_pk_add_f32 v[86:87], v[84:85], v[88:89] neg_lo:[0,1] neg_hi:[0,1]
	v_pk_add_f32 v[90:91], v[90:91], v[96:97] neg_lo:[0,1] neg_hi:[0,1]
	v_pk_add_f32 v[82:83], v[82:83], v[86:87] neg_lo:[0,1] neg_hi:[0,1]
	v_pk_add_f32 v[86:87], v[98:99], v[84:85]
	v_subrev_u32_e32 v122, 64, v71
	v_pk_add_f32 v[88:89], v[86:87], v[98:99] neg_lo:[0,1] neg_hi:[0,1]
	s_movk_i32 s13, 0x104
	v_pk_add_f32 v[94:95], v[86:87], v[88:89] neg_lo:[0,1] neg_hi:[0,1]
	v_pk_add_f32 v[84:85], v[84:85], v[88:89] neg_lo:[0,1] neg_hi:[0,1]
	v_pk_add_f32 v[94:95], v[98:99], v[94:95] neg_lo:[0,1] neg_hi:[0,1]
	v_pk_add_f32 v[88:89], v[90:91], v[82:83]
	v_pk_add_f32 v[84:85], v[84:85], v[94:95]
	v_pk_add_f32 v[94:95], v[88:89], v[90:91] neg_lo:[0,1] neg_hi:[0,1]
	v_pk_add_f32 v[84:85], v[88:89], v[84:85]
	v_pk_add_f32 v[96:97], v[88:89], v[94:95] neg_lo:[0,1] neg_hi:[0,1]
	v_pk_add_f32 v[88:89], v[86:87], v[84:85]
	v_pk_add_f32 v[90:91], v[90:91], v[96:97] neg_lo:[0,1] neg_hi:[0,1]
	v_pk_add_f32 v[82:83], v[82:83], v[94:95] neg_lo:[0,1] neg_hi:[0,1]
	v_pk_add_f32 v[86:87], v[88:89], v[86:87] neg_lo:[0,1] neg_hi:[0,1]
	v_pk_add_f32 v[82:83], v[82:83], v[90:91]
	v_pk_add_f32 v[84:85], v[84:85], v[86:87] neg_lo:[0,1] neg_hi:[0,1]
	v_add_u32_e32 v128, -16, v71
	v_pk_add_f32 v[82:83], v[82:83], v[84:85]
	v_lshl_or_b32 v71, v116, 1, 1
	v_pk_add_f32 v[82:83], v[88:89], v[82:83]
	v_lshlrev_b32_e32 v123, 9, v116
	v_cndmask_b32_e32 v66, v137, v82, vcc
	v_cmp_neq_f32_e32 vcc, s11, v114
	v_cmp_gt_i32_e64 s[0:1], s7, v120
	v_cmp_gt_i32_e64 s[4:5], s7, v118
	v_cndmask_b32_e32 v82, v137, v83, vcc
	v_cmp_ngt_f32_e32 vcc, -1.0, v114
	s_mov_b32 s18, 0
	v_lshl_add_u32 v146, v80, 2, s83
	v_cndmask_b32_e32 v82, v138, v82, vcc
	v_cmp_ngt_f32_e32 vcc, -1.0, v72
	s_waitcnt lgkmcnt(0)
	s_barrier
	v_cndmask_b32_e32 v66, v138, v66, vcc
	v_cmp_neq_f32_e32 vcc, -1.0, v72
	s_nop 1
	v_cndmask_b32_e32 v66, v135, v66, vcc
	v_cmp_neq_f32_e32 vcc, -1.0, v114
	s_nop 1
	v_cndmask_b32_e32 v82, v135, v82, vcc
	v_cmp_lt_f32_e64 vcc, |v114|, s15
	s_nop 1
	v_cndmask_b32_e32 v83, v82, v114, vcc
	v_cmp_lt_f32_e64 vcc, |v72|, s15
	s_nop 1
	v_cndmask_b32_e32 v82, v66, v72, vcc
	v_mul_f32_e64 v66, |v67|, s9
	v_exp_f32_e32 v108, v66
	v_pk_add_f32 v[106:107], v[64:65], v[82:83]
	v_max_f32_e64 v64, -v67, -v67
	v_max_f32_e32 v72, 0, v64
	v_add_f32_e32 v66, 1.0, v108
	v_add_f32_e32 v64, -1.0, v66
	v_sub_f32_e32 v65, v64, v66
	v_add_f32_e32 v65, 1.0, v65
	v_sub_f32_e32 v64, v108, v64
	v_add_f32_e32 v84, v64, v65
	v_frexp_mant_f32_e32 v67, v66
	v_cvt_f64_f32_e32 v[64:65], v66
	v_frexp_exp_i32_f64_e32 v64, v[64:65]
	v_cmp_gt_f32_e32 vcc, s10, v67
	s_nop 1
	v_subbrev_co_u32_e32 v64, vcc, 0, v64, vcc
	v_cmp_gt_f32_e32 vcc, s10, v112
	v_sub_u32_e32 v85, 0, v64
	v_readlane_b32 s10, v230, 37
	v_subbrev_co_u32_e32 v82, vcc, 0, v113, vcc
	v_sub_u32_e32 v67, 0, v82
	v_cvt_f32_i32_e32 v83, v82
	v_cvt_f32_i32_e32 v82, v64
	v_ldexp_f32 v64, v66, v85
	v_ldexp_f32 v66, v84, v85
	v_ldexp_f32 v65, v110, v67
	v_pk_mul_f32 v[84:85], v[82:83], s[20:21] op_sel_hi:[1,0]
	v_pk_add_f32 v[94:95], v[64:65], 1.0 op_sel_hi:[1,0]
	v_pk_fma_f32 v[86:87], v[82:83], s[20:21], v[84:85] op_sel_hi:[1,0,1] neg_lo:[0,0,1] neg_hi:[0,0,1]
	v_pk_add_f32 v[96:97], v[94:95], -1.0 op_sel_hi:[1,0]
	v_pk_fma_f32 v[82:83], v[82:83], s[22:23], v[86:87] op_sel_hi:[1,0,1]
	v_pk_add_f32 v[86:87], v[64:65], -1.0 op_sel_hi:[1,0]
	v_ldexp_f32 v67, v111, v67
	v_pk_add_f32 v[88:89], v[86:87], 1.0 op_sel_hi:[1,0]
	v_cmp_neq_f32_e32 vcc, s11, v108
	v_pk_add_f32 v[88:89], v[64:65], v[88:89] neg_lo:[0,1] neg_hi:[0,1]
	v_pk_add_f32 v[64:65], v[64:65], v[96:97] neg_lo:[0,1] neg_hi:[0,1]
	v_pk_add_f32 v[88:89], v[66:67], v[88:89]
	v_pk_add_f32 v[64:65], v[66:67], v[64:65]
	v_pk_add_f32 v[90:91], v[86:87], v[88:89]
	v_pk_add_f32 v[66:67], v[94:95], v[64:65]
	v_pk_add_f32 v[86:87], v[90:91], v[86:87] neg_lo:[0,1] neg_hi:[0,1]
	v_rcp_f32_e32 v97, v67
	v_rcp_f32_e32 v96, v66
	v_pk_add_f32 v[86:87], v[88:89], v[86:87] neg_lo:[0,1] neg_hi:[0,1]
	v_pk_add_f32 v[88:89], v[66:67], v[94:95] neg_lo:[0,1] neg_hi:[0,1]
	s_nop 0
	v_pk_add_f32 v[64:65], v[64:65], v[88:89] neg_lo:[0,1] neg_hi:[0,1]
	v_pk_mul_f32 v[88:89], v[90:91], v[96:97]
	s_nop 0
	v_pk_mul_f32 v[94:95], v[66:67], v[88:89]
	s_nop 0
	v_pk_fma_f32 v[98:99], v[88:89], v[66:67], v[94:95] neg_lo:[0,0,1] neg_hi:[0,0,1]
	s_nop 0
	v_pk_fma_f32 v[98:99], v[88:89], v[64:65], v[98:99]
	s_nop 0
	v_pk_add_f32 v[100:101], v[94:95], v[98:99]
	s_nop 0
	v_pk_add_f32 v[102:103], v[90:91], v[100:101] neg_lo:[0,1] neg_hi:[0,1]
	v_pk_add_f32 v[94:95], v[100:101], v[94:95] neg_lo:[0,1] neg_hi:[0,1]
	v_pk_add_f32 v[90:91], v[90:91], v[102:103] neg_lo:[0,1] neg_hi:[0,1]
	s_nop 0
	v_pk_add_f32 v[90:91], v[90:91], v[100:101] neg_lo:[0,1] neg_hi:[0,1]
	s_nop 0
	v_pk_add_f32 v[86:87], v[86:87], v[90:91]
	v_pk_add_f32 v[90:91], v[94:95], v[98:99] neg_lo:[0,1] neg_hi:[0,1]
	s_nop 0
	v_pk_add_f32 v[86:87], v[90:91], v[86:87]
	s_nop 0
	v_pk_add_f32 v[90:91], v[102:103], v[86:87]
	s_nop 0
	v_pk_mul_f32 v[94:95], v[96:97], v[90:91]
	v_pk_add_f32 v[102:103], v[102:103], v[90:91] neg_lo:[0,1] neg_hi:[0,1]
	v_pk_mul_f32 v[98:99], v[66:67], v[94:95]
; DI void lru_unit(const Params& p, unsigned char* smem, int unit) {
;     ...
;     for (int j = 0; j < 4; ++j) {
;         const int ch = n * 128 + half * 64 + et * 16 + fq * 4 + j;
;         br[j] = p.b_r[ch]; bi[j] = p.b_i[ch];
;         const float l = p.lam[ch];
;         sp[j] = fmaxf(-l, 0.f) + log1pf(__expf(-fabsf(l)));
;     }
;     ...
;     for (int c = 0; c < 65; ++c) {
;         const int base = c == 0 ? MR : b * 4096 + (c - 1) * 64;
;         const int nv = c == 0 ? 16 : 64;
; #pragma unroll
;         for (int i = 0; i < 3; ++i) {
;             const int vid = tid + 512 * i, ri = vid >> 4, part = vid & 15;
;             if (ri < 67) *(u32x4*)(sRaw + ri * 128 + part * 8) = rr_[i];
	v_pk_add_f32 v[86:87], v[86:87], v[102:103]
	v_pk_fma_f32 v[66:67], v[94:95], v[66:67], v[98:99] neg_lo:[0,0,1] neg_hi:[0,0,1]
	s_nop 0
	v_pk_fma_f32 v[64:65], v[94:95], v[64:65], v[66:67]
	s_nop 0
	v_pk_add_f32 v[66:67], v[98:99], v[64:65]
	s_nop 0
	v_pk_add_f32 v[100:101], v[90:91], v[66:67] neg_lo:[0,1] neg_hi:[0,1]
	v_pk_add_f32 v[98:99], v[66:67], v[98:99] neg_lo:[0,1] neg_hi:[0,1]
	v_pk_add_f32 v[90:91], v[90:91], v[100:101] neg_lo:[0,1] neg_hi:[0,1]
	v_pk_add_f32 v[64:65], v[98:99], v[64:65] neg_lo:[0,1] neg_hi:[0,1]
	v_pk_add_f32 v[66:67], v[90:91], v[66:67] neg_lo:[0,1] neg_hi:[0,1]
	s_nop 0
	v_pk_add_f32 v[66:67], v[86:87], v[66:67]
	s_nop 0
	v_pk_add_f32 v[64:65], v[64:65], v[66:67]
	v_pk_add_f32 v[66:67], v[88:89], v[94:95]
	v_pk_add_f32 v[64:65], v[100:101], v[64:65]
	v_pk_add_f32 v[86:87], v[66:67], v[88:89] neg_lo:[0,1] neg_hi:[0,1]
	v_pk_mul_f32 v[64:65], v[96:97], v[64:65]
	v_pk_add_f32 v[86:87], v[94:95], v[86:87] neg_lo:[0,1] neg_hi:[0,1]
	s_nop 0
	v_pk_add_f32 v[64:65], v[86:87], v[64:65]
	s_nop 0
	v_pk_add_f32 v[86:87], v[66:67], v[64:65]
	s_nop 0
	v_pk_mul_f32 v[88:89], v[86:87], v[86:87]
	v_pk_add_f32 v[66:67], v[86:87], v[66:67] neg_lo:[0,1] neg_hi:[0,1]
	v_pk_fma_f32 v[90:91], v[88:89], s[6:7], v[92:93] op_sel_hi:[1,0,0]
	v_pk_add_f32 v[64:65], v[64:65], v[66:67] neg_lo:[0,1] neg_hi:[0,1]
	v_ldexp_f32 v67, v87, 1
	v_pk_fma_f32 v[90:91], v[88:89], v[90:91], s[16:17] op_sel_hi:[1,1,0]
	v_ldexp_f32 v66, v86, 1
	v_pk_mul_f32 v[86:87], v[86:87], v[88:89]
	v_ldexp_f32 v65, v65, 1
	v_pk_mul_f32 v[86:87], v[86:87], v[90:91]
	v_ldexp_f32 v64, v64, 1
	v_pk_add_f32 v[88:89], v[66:67], v[86:87]
	s_cselect_b64 s[16:17], -1, 0
	v_pk_add_f32 v[66:67], v[88:89], v[66:67] neg_lo:[0,1] neg_hi:[0,1]
	v_mov_b32_e32 v97, v89
	v_pk_add_f32 v[66:67], v[86:87], v[66:67] neg_lo:[0,1] neg_hi:[0,1]
	s_lshl_b32 s92, s14, 1
	v_pk_add_f32 v[64:65], v[64:65], v[66:67]
	v_pk_add_f32 v[66:67], v[84:85], v[82:83]
	v_pk_add_f32 v[86:87], v[88:89], v[64:65]
	v_pk_add_f32 v[84:85], v[66:67], v[84:85] neg_lo:[0,1] neg_hi:[0,1]
	v_pk_add_f32 v[90:91], v[66:67], v[86:87]
	v_mov_b32_e32 v95, v87
	v_pk_add_f32 v[92:93], v[90:91], v[66:67] neg_lo:[0,1] neg_hi:[0,1]
	v_mov_b32_e32 v94, v90
	v_mov_b32_e32 v96, v92
	v_pk_add_f32 v[94:95], v[94:95], v[96:97] neg_lo:[0,1] neg_hi:[0,1]
	v_mov_b32_e32 v96, v66
	v_mov_b32_e32 v97, v65
	v_pk_add_f32 v[92:93], v[86:87], v[92:93] neg_lo:[0,1] neg_hi:[0,1]
	v_pk_add_f32 v[82:83], v[82:83], v[84:85] neg_lo:[0,1] neg_hi:[0,1]
	v_pk_add_f32 v[94:95], v[96:97], v[94:95] neg_lo:[0,1] neg_hi:[0,1]
	v_mov_b32_e32 v93, v83
	v_pk_add_f32 v[84:85], v[92:93], v[94:95]
	v_mov_b32_e32 v92, v86
	v_mov_b32_e32 v93, v91
	v_mov_b32_e32 v89, v67
	v_pk_add_f32 v[88:89], v[92:93], v[88:89] neg_lo:[0,1] neg_hi:[0,1]
	v_mov_b32_e32 v65, v87
	v_pk_add_f32 v[92:93], v[90:91], v[88:89] neg_lo:[0,1] neg_hi:[0,1]
	v_pk_add_f32 v[64:65], v[64:65], v[88:89] neg_lo:[0,1] neg_hi:[0,1]
	v_pk_add_f32 v[66:67], v[66:67], v[92:93] neg_lo:[0,1] neg_hi:[0,1]
	v_mov_b32_e32 v87, v85
	v_mov_b32_e32 v66, v82
	v_pk_add_f32 v[66:67], v[64:65], v[66:67]
	v_mov_b32_e32 v65, v95
	v_mov_b32_e32 v86, v66
	v_pk_add_f32 v[88:89], v[86:87], v[82:83] neg_lo:[0,1] neg_hi:[0,1]
	v_pk_add_f32 v[66:67], v[84:85], v[66:67]
	v_pk_add_f32 v[86:87], v[86:87], v[88:89] neg_lo:[0,1] neg_hi:[0,1]
	v_pk_add_f32 v[64:65], v[64:65], v[88:89] neg_lo:[0,1] neg_hi:[0,1]
	v_pk_add_f32 v[82:83], v[82:83], v[86:87] neg_lo:[0,1] neg_hi:[0,1]
	v_cmp_gt_i32_e64 s[6:7], s7, v116
	v_pk_add_f32 v[64:65], v[64:65], v[82:83]
	v_pk_add_f32 v[82:83], v[90:91], v[66:67]
	s_nop 0
	v_pk_add_f32 v[84:85], v[82:83], v[90:91] neg_lo:[0,1] neg_hi:[0,1]
	s_nop 0
	v_pk_add_f32 v[66:67], v[66:67], v[84:85] neg_lo:[0,1] neg_hi:[0,1]
	s_nop 0
	v_pk_add_f32 v[64:65], v[64:65], v[66:67]
	v_lshrrev_b32_e32 v67, 3, v75
	v_pk_add_f32 v[64:65], v[82:83], v[64:65]
	v_cmp_eq_u32_e64 s[8:9], s8, v67
	v_cndmask_b32_e32 v64, v137, v64, vcc
	v_cmp_neq_f32_e32 vcc, s11, v81
	v_lshlrev_b32_e32 v67, 2, v79
	v_add_u32_e32 v124, s10, v67
	v_cndmask_b32_e32 v65, v137, v65, vcc
	v_cmp_ngt_f32_e32 vcc, -1.0, v81
	v_mul_lo_u32 v79, v71, s35
	s_nop 0
	v_cndmask_b32_e32 v65, v138, v65, vcc
	v_cmp_ngt_f32_e32 vcc, -1.0, v108
	s_nop 1
	v_cndmask_b32_e32 v64, v138, v64, vcc
	v_cmp_neq_f32_e32 vcc, -1.0, v108
	s_nop 1
	v_cndmask_b32_e32 v64, v135, v64, vcc
	v_cmp_neq_f32_e32 vcc, -1.0, v81
	s_nop 1
	v_cndmask_b32_e32 v65, v135, v65, vcc
	v_cmp_lt_f32_e64 vcc, |v81|, s15
	s_nop 1
	v_cndmask_b32_e32 v65, v65, v81, vcc
	v_cmp_lt_f32_e64 vcc, |v108|, s15
	v_lshlrev_b32_e32 v81, 8, v71
	v_readlane_b32 s15, v230, 38
	v_cndmask_b32_e32 v64, v64, v108, vcc
	v_pk_add_f32 v[108:109], v[72:73], v[64:65]
	v_or_b32_e32 v72, v77, v75
	v_mul_u32_u24_e32 v72, 0x110, v72
	v_lshlrev_b32_e32 v73, 4, v74
	v_add3_u32 v125, 0, v72, v73
	v_lshlrev_b32_e32 v73, 2, v77
	v_lshlrev_b32_e32 v74, 2, v78
	v_cmp_gt_i32_e32 vcc, 64, v117
	v_and_b32_e32 v72, 48, v69
	v_add3_u32 v126, s10, v73, v74
	v_cmp_gt_u32_e64 s[10:11], 64, v69
	v_cndmask_b32_e32 v69, 0, v117, vcc
	v_add_u32_e32 v127, v122, v69
	v_mul_lo_u32 v69, v117, s13
	s_movk_i32 s13, 0x220
	v_mul_lo_u32 v78, v116, s13
	s_movk_i32 s13, 0xffe0
	v_and_or_b32 v71, v117, s13, v75
	v_lshlrev_b32_e32 v65, 4, v75
	v_mul_lo_u32 v75, v71, s35
	v_lshlrev_b32_e32 v129, 8, v71
	v_lshl_add_u32 v71, v71, 6, v71
	s_add_u32 s13, s74, s92
	v_add_lshl_u32 v71, v76, v71, 2
	s_addc_u32 s14, s75, 0
	s_lshl_b32 s12, s12, 1
	v_add_u32_e32 v130, s83, v71
	v_add_u32_e32 v131, s15, v71
	v_add_u32_e32 v82, 0x1040, v71
	v_add_u32_e32 v71, 0x1048, v71
	s_add_u32 s12, s13, s12
	v_add_u32_e32 v64, 0, v123
	v_add_u32_e32 v66, 0, v65
	v_add_u32_e32 v72, 0, v72
	v_add_u32_e32 v67, s15, v67
	v_lshlrev_b32_e32 v73, 8, v116
	v_lshlrev_b32_e32 v74, 8, v118
	v_lshlrev_b32_e32 v77, 8, v120
	v_or_b32_e32 v76, 0x1000, v129
	v_add_u32_e32 v144, s83, v71
	v_add_u32_e32 v145, s15, v71
	s_addc_u32 s13, s14, 0
	v_mov_b32_e32 v71, v105
	v_add_u32_e32 v132, 4, v131
	v_add_u32_e32 v133, 12, v131
	v_add_u32_e32 v142, s83, v82
	v_add_u32_e32 v143, s15, v82
	v_pk_mov_b32 v[110:111], v[106:107], v[108:109] op_sel:[1,0]
	v_pk_mov_b32 v[112:113], v[108:109], v[106:107] op_sel:[1,0]
	v_lshl_add_u64 v[114:115], s[12:13], 0, v[70:71]
	v_add_u32_e32 v147, v68, v73
	v_add_u32_e32 v148, v68, v74
	v_add_u32_e32 v149, v68, v77
	v_add_u32_e32 v150, v64, v65
	v_add_u32_e32 v151, v66, v78
	v_add_u32_e32 v152, v66, v79
	v_add_u32_e32 v153, v124, v81
	v_add_u32_e32 v154, v72, v75
	v_add_u32_e32 v155, v126, v76
	v_add_u32_e32 v156, v67, v69
	s_waitcnt vmcnt(0)
	s_branch .LBB0_338
.LBB0_337:
	s_or_b64 exec, exec, s[12:13]
	s_cmp_eq_u32 s18, 0
	s_cbranch_scc1 .Llru_drain_all
	s_waitcnt vmcnt(1)
	s_branch .Llru_drain_done

; DI void lru_unit(const Params& p, unsigned char* smem, int unit) {
;     ...
;     for (int c = 0; c < 65; ++c) {
;         const int base = c == 0 ? MR : b * 4096 + (c - 1) * 64;
;         const int nv = c == 0 ? 16 : 64;
; #pragma unroll
;         for (int i = 0; i < 3; ++i) {
;             const int vid = tid + 512 * i, ri = vid >> 4, part = vid & 15;
;             if (ri < 67) *(u32x4*)(sRaw + ri * 128 + part * 8) = rr_[i];
.Llru_drain_done:
	v_mov_b64_e32 v[48:49], v[64:65]
	s_cmpk_lg_i32 s19, 0x41
	s_mov_b32 s18, s19
	v_mov_b64_e32 v[50:51], v[66:67]
	s_cbranch_scc0 .LBB0_361
.LBB0_338:
	s_and_saveexec_b64 s[12:13], s[6:7]
	s_cbranch_execz .LBB0_359
	s_waitcnt vmcnt(1)
	ds_write_b128 v147, v[56:59] offset:34816
	s_or_b64 exec, exec, s[12:13]
	s_and_saveexec_b64 s[12:13], s[4:5]
	s_cbranch_execnz .LBB0_360

; DI void lru_unit(const Params& p, unsigned char* smem, int unit) {
;     ...
;         const int t0 = c == 0 ? 0 : 16 + (c - 1) * 64;
;         {
;             const int t = tid >> 3, nvc = c == 0 ? 16 : 64;
;             const size_t row = (size_t)((c == 0 ? MR : b * 4096 + (c - 1) * 64) + (t < nvc ? t : 0));
;             rg_ = *(const u32x4*)(OG + row * 2048 + 1024 + n * 128 + half * 64 + (tid & 7) * 8);
;         }
; #pragma unroll
;         for (int i = 0; i < 3; ++i) {
;             const int vid = tid + 512 * i, ri = vid >> 4, part = vid & 15;
;             const int tt = t0 - 3 + ri;
;             u32x4 v = (u32x4){0u, 0u, 0u, 0u};
;             if (ri < 67 && tt >= 0 && tt < TSEQ) {
;                 const size_t row = tt < 16 ? (size_t)(MR + tt) : (size_t)(b * 4096 + tt - 16);
;                 v = *(const u32x4*)(T1 + row * 4096 + 3072 + n * 128 + part * 8);
;             }
;             rr_[i] = v;
;         }
;     ...
;         for (int i = 0; i < 3; ++i) {
;             const int vid = tid + 512 * i, ri = vid >> 4, part = vid & 15;
;             if (ri < 67) *(u32x4*)(sRaw + ri * 128 + part * 8) = rr_[i];
;         }
;         __syncthreads();
;         const u32x4 gv = rg_;
;         if (c + 1 < 65) issue_loads(c + 1);
.LBB0_341:
	s_waitcnt vmcnt(1)
	ds_write_b128 v149, v[60:63] offset:34816
.LBB0_342:
	s_or_b64 exec, exec, s[12:13]
	s_add_i32 s19, s18, 1
	s_waitcnt vmcnt(1)
	v_mov_b64_e32 v[66:67], v[50:51]
	s_cmp_eq_u32 s18, 64
	v_mov_b64_e32 v[64:65], v[48:49]
	s_waitcnt lgkmcnt(0)
	s_barrier
	s_cbranch_scc1 .LBB0_350
	s_lshl_b32 s12, s19, 6
	v_add_u32_e32 v52, s12, v127
	v_ashrrev_i32_e32 v53, 31, v52
	v_lshlrev_b64 v[52:53], 12, v[52:53]
	v_lshl_add_u64 v[52:53], v[114:115], 0, v[52:53]
	global_load_dwordx4 v[64:67], v[52:53], off offset:2048
	s_sub_i32 s14, s12, 51
	v_add_u32_e32 v60, s14, v116
	v_mov_b32_e32 v54, v105
	v_mov_b32_e32 v55, v105
	v_cmp_gt_u32_e32 vcc, s87, v60
	v_mov_b32_e32 v52, 0
	v_mov_b32_e32 v53, v105
	v_mov_b64_e32 v[58:59], v[54:55]
	s_and_b64 s[20:21], s[6:7], vcc
	v_mov_b64_e32 v[56:57], v[52:53]
	s_and_saveexec_b64 s[12:13], s[20:21]
	s_cbranch_execz .LBB0_345
	v_add_u32_e32 v58, v60, v128
	v_or_b32_e32 v56, 0x8000, v60
	v_ashrrev_i32_e32 v57, 31, v58
	v_cmp_gt_u32_e32 vcc, 16, v60
	s_nop 1
	v_cndmask_b32_e64 v57, v57, 0, vcc
	v_cndmask_b32_e32 v56, v58, v56, vcc
	v_lshlrev_b64 v[56:57], 13, v[56:57]
	v_lshl_add_u64 v[56:57], s[66:67], 0, v[56:57]
	v_lshl_add_u64 v[56:57], v[56:57], 0, s[92:93]
	v_lshl_add_u64 v[56:57], v[56:57], 0, v[104:105]
	v_add_co_u32_e32 v56, vcc, 0x1000, v56
	s_nop 1
	v_addc_co_u32_e32 v57, vcc, 0, v57, vcc
	global_load_dwordx4 v[56:59], v[56:57], off offset:2048

; DI void lru_unit(const Params& p, unsigned char* smem, int unit) {
;     ...
; #pragma unroll
;         for (int i = 0; i < 3; ++i) {
;             const int vid = tid + 512 * i, ri = vid >> 4, part = vid & 15;
;             if (ri < 67) *(u32x4*)(sRaw + ri * 128 + part * 8) = rr_[i];
.LBB0_360:
	s_waitcnt vmcnt(1)
	ds_write_b128 v148, v[52:55] offset:34816
	s_or_b64 exec, exec, s[12:13]
	s_and_saveexec_b64 s[12:13], s[0:1]
	s_cbranch_execnz .LBB0_341
	s_branch .LBB0_342

; DI void mlstm_unit(const Params& p, unsigned char* smem, int unit) {
;     ...
;         if (wid == 0 && c + 1 < 65) gate_scan(gbuf + ((c + 1) & 1) * 336);
;         __syncthreads();
;     }
.LBB0_375:
	s_or_b64 exec, exec, s[76:77]
	s_add_i32 s97, s97, 64
	s_add_i32 s96, s96, 1
	v_add_u32_e32 v124, 0x100, v124
	s_cmpk_eq_i32 s97, 64
	s_cbranch_scc1 .Lml_drain_all
	s_waitcnt vmcnt(2)
	s_branch .Lml_drain_done

; DI void mlstm_unit(const Params& p, unsigned char* smem, int unit) {
;     ...
;         const u32x2 og0 = rog[0], og1 = rog[1];
;     ...
;         if (wid == 0 && c + 1 < 65) gate_scan(gbuf + ((c + 1) & 1) * 336);
;         __syncthreads();
;     }
.Lml_drain_done:
	v_mov_b64_e32 v[132:133], v[126:127]
	v_mov_b64_e32 v[130:131], v[128:129]
	s_cmpk_eq_i32 s97, 0x1040
	s_waitcnt lgkmcnt(0)
	s_barrier
	s_cbranch_scc1 .LBB0_325
